# P0 GEMV arithmetic: 128 v_fmac_f32 per 16-row step instead of 64 v_pk_fma_f32 plus ~100 operand-pair shuffles
# speedup vs baseline: 1.0019x; 1.0019x over previous
; __device__ __forceinline__ void p0_prologue(const Args& A, char* lds, int vcu, int G) {
;     ...
; #pragma unroll 16
;         for (int k = 0; k < 128; ++k) { const float w = __builtin_nontemporal_load(&wp[(size_t)k * 3072]);
; #pragma unroll
;             for (int b = 0; b < 8; ++b) acc[b] += sc[b * 128 + k] * w; }
.LBB0_293:
	v_mov_b32_e32 v20, s21
	ds_read_b128 v[22:25], v20
	ds_read_b128 v[26:29], v20 offset:16
	ds_read_b128 v[30:33], v20 offset:512
	ds_read_b128 v[34:37], v20 offset:528
	ds_read_b128 v[38:41], v20 offset:1024
	ds_read_b128 v[42:45], v20 offset:1040
	ds_read_b128 v[46:49], v20 offset:1536
	ds_read_b128 v[50:53], v20 offset:1552
	ds_read_b128 v[54:57], v20 offset:2048
	ds_read_b128 v[58:61], v20 offset:2064
	ds_read_b128 v[62:65], v20 offset:2560
	ds_read_b128 v[66:69], v20 offset:2576
	ds_read_b128 v[70:73], v20 offset:3072
	ds_read_b128 v[74:77], v20 offset:3088
	ds_read_b128 v[78:81], v20 offset:3584
	ds_read_b128 v[82:85], v20 offset:3600
	ds_read_b128 v[86:89], v20 offset:32
	ds_read_b128 v[90:93], v20 offset:48
	ds_read_b128 v[94:97], v20 offset:544
	ds_read_b128 v[98:101], v20 offset:560
	ds_read_b128 v[102:105], v20 offset:1056
	ds_read_b128 v[106:109], v20 offset:1072
	ds_read_b128 v[110:113], v20 offset:1568
	ds_read_b128 v[114:117], v20 offset:1584
	ds_read_b128 v[118:121], v20 offset:2080
	ds_read_b128 v[122:125], v20 offset:2096
	ds_read_b128 v[126:129], v20 offset:2592
	ds_read_b128 v[130:133], v20 offset:2608
	ds_read_b128 v[134:137], v20 offset:3104
	ds_read_b128 v[138:141], v20 offset:3120
	ds_read_b128 v[142:145], v20 offset:3616
	ds_read_b128 v[146:149], v20 offset:3632
	s_waitcnt lgkmcnt(0)
	s_cmp_eq_u32 s22, 0x30000
	s_cbranch_scc1 .Lgv_it1
	s_cmp_eq_u32 s22, 0x60000
	s_cbranch_scc1 .Lgv_it2
	s_cmp_eq_u32 s22, 0x90000
	s_cbranch_scc1 .Lgv_it3
	s_cmp_eq_u32 s22, 0xc0000
	s_cbranch_scc1 .Lgv_it4
	s_cmp_eq_u32 s22, 0xf0000
	s_cbranch_scc1 .Lgv_it5
	s_cmp_eq_u32 s22, 0x120000
	s_cbranch_scc1 .Lgv_it6
	s_cmp_eq_u32 s22, 0x150000
	s_cbranch_scc1 .Lgv_it7
	s_waitcnt vmcnt(32)
	v_mov_b32_e32 v150, v180
	v_mov_b32_e32 v152, v181
	v_mov_b32_e32 v154, v182
	v_mov_b32_e32 v156, v183
	v_mov_b32_e32 v158, v184
	v_mov_b32_e32 v160, v185
	v_mov_b32_e32 v162, v186
	v_mov_b32_e32 v164, v187
	v_mov_b32_e32 v166, v188
	v_mov_b32_e32 v20, v189
	v_mov_b32_e32 v168, v190
	v_mov_b32_e32 v170, v191
	v_mov_b32_e32 v172, v192
	v_mov_b32_e32 v174, v193
	v_mov_b32_e32 v176, v194
	v_mov_b32_e32 v12, v195
	s_add_u32 s100, s98, 0x90000
	s_addc_u32 s101, s99, 0
	global_load_dword v180, v255, s[100:101] nt
	s_add_u32 s100, s98, 0x93000
	s_addc_u32 s101, s99, 0
	global_load_dword v181, v255, s[100:101] nt
	s_add_u32 s100, s98, 0x96000
	s_addc_u32 s101, s99, 0
	global_load_dword v182, v255, s[100:101] nt
	s_add_u32 s100, s98, 0x99000
	s_addc_u32 s101, s99, 0
	global_load_dword v183, v255, s[100:101] nt
	s_add_u32 s100, s98, 0x9c000
	s_addc_u32 s101, s99, 0
	global_load_dword v184, v255, s[100:101] nt
	s_add_u32 s100, s98, 0x9f000
	s_addc_u32 s101, s99, 0
	global_load_dword v185, v255, s[100:101] nt
	s_add_u32 s100, s98, 0xa2000
	s_addc_u32 s101, s99, 0
	global_load_dword v186, v255, s[100:101] nt
	s_add_u32 s100, s98, 0xa5000
	s_addc_u32 s101, s99, 0
	global_load_dword v187, v255, s[100:101] nt
	s_add_u32 s100, s98, 0xa8000
	s_addc_u32 s101, s99, 0
	global_load_dword v188, v255, s[100:101] nt
	s_add_u32 s100, s98, 0xab000
	s_addc_u32 s101, s99, 0
	global_load_dword v189, v255, s[100:101] nt
	s_add_u32 s100, s98, 0xae000
	s_addc_u32 s101, s99, 0
	global_load_dword v190, v255, s[100:101] nt
	s_add_u32 s100, s98, 0xb1000
	s_addc_u32 s101, s99, 0
	global_load_dword v191, v255, s[100:101] nt
	s_add_u32 s100, s98, 0xb4000
	s_addc_u32 s101, s99, 0
	global_load_dword v192, v255, s[100:101] nt
	s_add_u32 s100, s98, 0xb7000
	s_addc_u32 s101, s99, 0
	global_load_dword v193, v255, s[100:101] nt
	s_add_u32 s100, s98, 0xba000
	s_addc_u32 s101, s99, 0
	global_load_dword v194, v255, s[100:101] nt
	s_add_u32 s100, s98, 0xbd000
	s_addc_u32 s101, s99, 0
	global_load_dword v195, v255, s[100:101] nt
	s_branch .Lgv_join

; __device__ __forceinline__ void p0_prologue(const Args& A, char* lds, int vcu, int G) {
;     ...
; #pragma unroll 16
;         for (int k = 0; k < 128; ++k) { const float w = __builtin_nontemporal_load(&wp[(size_t)k * 3072]);
; #pragma unroll
;             for (int b = 0; b < 8; ++b) acc[b] += sc[b * 128 + k] * w; }
; #pragma unroll
;         for (int b = 0; b < 8; ++b) modp[((size_t)(kc * 2 + l) * 8 + b) * 3072 + col] = acc[b];
.Lgv_join:
	v_fmac_f32_e32 v10, v150, v22
	v_fmac_f32_e32 v11, v150, v30
	v_fmac_f32_e32 v8, v150, v38
	v_fmac_f32_e32 v9, v150, v46
	v_fmac_f32_e32 v6, v150, v54
	v_fmac_f32_e32 v7, v150, v62
	v_fmac_f32_e32 v4, v150, v70
	v_fmac_f32_e32 v5, v150, v78
	v_fmac_f32_e32 v10, v152, v23
	v_fmac_f32_e32 v11, v152, v31
	v_fmac_f32_e32 v8, v152, v39
	v_fmac_f32_e32 v9, v152, v47
	v_fmac_f32_e32 v6, v152, v55
	v_fmac_f32_e32 v7, v152, v63
	v_fmac_f32_e32 v4, v152, v71
	v_fmac_f32_e32 v5, v152, v79
	v_fmac_f32_e32 v10, v154, v24
	v_fmac_f32_e32 v11, v154, v32
	v_fmac_f32_e32 v8, v154, v40
	v_fmac_f32_e32 v9, v154, v48
	v_fmac_f32_e32 v6, v154, v56
	v_fmac_f32_e32 v7, v154, v64
	v_fmac_f32_e32 v4, v154, v72
	v_fmac_f32_e32 v5, v154, v80
	v_fmac_f32_e32 v10, v156, v25
	v_fmac_f32_e32 v11, v156, v33
	v_fmac_f32_e32 v8, v156, v41
	v_fmac_f32_e32 v9, v156, v49
	v_fmac_f32_e32 v6, v156, v57
	v_fmac_f32_e32 v7, v156, v65
	v_fmac_f32_e32 v4, v156, v73
	v_fmac_f32_e32 v5, v156, v81
	v_fmac_f32_e32 v10, v158, v26
	v_fmac_f32_e32 v11, v158, v34
	v_fmac_f32_e32 v8, v158, v42
	v_fmac_f32_e32 v9, v158, v50
	v_fmac_f32_e32 v6, v158, v58
	v_fmac_f32_e32 v7, v158, v66
	v_fmac_f32_e32 v4, v158, v74
	v_fmac_f32_e32 v5, v158, v82
	v_fmac_f32_e32 v10, v160, v27
	v_fmac_f32_e32 v11, v160, v35
	v_fmac_f32_e32 v8, v160, v43
	v_fmac_f32_e32 v9, v160, v51
	v_fmac_f32_e32 v6, v160, v59
	v_fmac_f32_e32 v7, v160, v67
	v_fmac_f32_e32 v4, v160, v75
	v_fmac_f32_e32 v5, v160, v83
	v_fmac_f32_e32 v10, v162, v28
	v_fmac_f32_e32 v11, v162, v36
	v_fmac_f32_e32 v8, v162, v44
	v_fmac_f32_e32 v9, v162, v52
	v_fmac_f32_e32 v6, v162, v60
	v_fmac_f32_e32 v7, v162, v68
	v_fmac_f32_e32 v4, v162, v76
	v_fmac_f32_e32 v5, v162, v84
	v_fmac_f32_e32 v10, v164, v29
	v_fmac_f32_e32 v11, v164, v37
	v_fmac_f32_e32 v8, v164, v45
	v_fmac_f32_e32 v9, v164, v53
	v_fmac_f32_e32 v6, v164, v61
	v_fmac_f32_e32 v7, v164, v69
	v_fmac_f32_e32 v4, v164, v77
	v_fmac_f32_e32 v5, v164, v85
	v_fmac_f32_e32 v10, v166, v86
	v_fmac_f32_e32 v11, v166, v94
	v_fmac_f32_e32 v8, v166, v102
	v_fmac_f32_e32 v9, v166, v110
	v_fmac_f32_e32 v6, v166, v118
	v_fmac_f32_e32 v7, v166, v126
	v_fmac_f32_e32 v4, v166, v134
	v_fmac_f32_e32 v5, v166, v142
	v_fmac_f32_e32 v10, v20, v87
	v_fmac_f32_e32 v11, v20, v95
	v_fmac_f32_e32 v8, v20, v103
	v_fmac_f32_e32 v9, v20, v111
	v_fmac_f32_e32 v6, v20, v119
	v_fmac_f32_e32 v7, v20, v127
	v_fmac_f32_e32 v4, v20, v135
	v_fmac_f32_e32 v5, v20, v143
	v_fmac_f32_e32 v10, v168, v88
	v_fmac_f32_e32 v11, v168, v96
	v_fmac_f32_e32 v8, v168, v104
	v_fmac_f32_e32 v9, v168, v112
	v_fmac_f32_e32 v6, v168, v120
	v_fmac_f32_e32 v7, v168, v128
	v_fmac_f32_e32 v4, v168, v136
	v_fmac_f32_e32 v5, v168, v144
	v_fmac_f32_e32 v10, v170, v89
	v_fmac_f32_e32 v11, v170, v97
	v_fmac_f32_e32 v8, v170, v105
	v_fmac_f32_e32 v9, v170, v113
	v_fmac_f32_e32 v6, v170, v121
	v_fmac_f32_e32 v7, v170, v129
	v_fmac_f32_e32 v4, v170, v137
	v_fmac_f32_e32 v5, v170, v145
	v_fmac_f32_e32 v10, v172, v90
	v_fmac_f32_e32 v11, v172, v98
	v_fmac_f32_e32 v8, v172, v106
	v_fmac_f32_e32 v9, v172, v114
	v_fmac_f32_e32 v6, v172, v122
	v_fmac_f32_e32 v7, v172, v130
	v_fmac_f32_e32 v4, v172, v138
	v_fmac_f32_e32 v5, v172, v146
	v_fmac_f32_e32 v10, v174, v91
	v_fmac_f32_e32 v11, v174, v99
	v_fmac_f32_e32 v8, v174, v107
	v_fmac_f32_e32 v9, v174, v115
	v_fmac_f32_e32 v6, v174, v123
	v_fmac_f32_e32 v7, v174, v131
	v_fmac_f32_e32 v4, v174, v139
	v_fmac_f32_e32 v5, v174, v147
	v_fmac_f32_e32 v10, v176, v92
	v_fmac_f32_e32 v11, v176, v100
	v_fmac_f32_e32 v8, v176, v108
	v_fmac_f32_e32 v9, v176, v116
	v_fmac_f32_e32 v6, v176, v124
	v_fmac_f32_e32 v7, v176, v132
	v_fmac_f32_e32 v4, v176, v140
	v_fmac_f32_e32 v5, v176, v148
	v_fmac_f32_e32 v10, v12, v93
	v_fmac_f32_e32 v11, v12, v101
	v_fmac_f32_e32 v8, v12, v109
	v_fmac_f32_e32 v9, v12, v117
	v_fmac_f32_e32 v6, v12, v125
	v_fmac_f32_e32 v7, v12, v133
	v_fmac_f32_e32 v4, v12, v141
	v_fmac_f32_e32 v5, v12, v149
	s_add_u32 s22, s22, 0x30000
	s_addc_u32 s23, s23, 0
	s_add_i32 s21, s21, 64
	s_cmp_eq_u32 s22, 0x180000
	s_cbranch_scc0 .LBB0_293
	s_lshl_b32 s21, s54, 1
	s_add_i32 s21, s21, s20
	v_lshl_add_u64 v[0:1], v[0:1], 2, s[40:41]
	v_mad_i64_i32 v[0:1], s[20:21], s21, v19, v[0:1]
	v_add_co_u32_e32 v2, vcc, 0x3000, v0
	flat_store_dword v[0:1], v10
	s_nop 0
	v_addc_co_u32_e32 v3, vcc, 0, v1, vcc
	flat_store_dword v[2:3], v11
	v_add_co_u32_e32 v2, vcc, 0x6000, v0
	s_add_i32 s53, s53, s38
	s_nop 0
	v_addc_co_u32_e32 v3, vcc, 0, v1, vcc
	flat_store_dword v[2:3], v8
	v_add_co_u32_e32 v2, vcc, 0x9000, v0
	s_cmpk_gt_i32 s53, 0x5f
	s_nop 0
	v_addc_co_u32_e32 v3, vcc, 0, v1, vcc
	flat_store_dword v[2:3], v9
	v_add_co_u32_e32 v2, vcc, 0xc000, v0
	s_nop 1
	v_addc_co_u32_e32 v3, vcc, 0, v1, vcc
	flat_store_dword v[2:3], v6
	v_add_co_u32_e32 v2, vcc, 0xf000, v0
	s_nop 1
	v_addc_co_u32_e32 v3, vcc, 0, v1, vcc
	flat_store_dword v[2:3], v7
	v_add_co_u32_e32 v2, vcc, 0x12000, v0
	s_nop 1
	v_addc_co_u32_e32 v3, vcc, 0, v1, vcc
	v_add_co_u32_e32 v0, vcc, 0x15000, v0
	flat_store_dword v[2:3], v4
	s_nop 0
	v_addc_co_u32_e32 v1, vcc, 0, v1, vcc
	flat_store_dword v[0:1], v5
	s_cbranch_scc0 .LBB0_289
